# XB4: XB1 + acquire L1 invalidate issued early (before the first poll / right after the top-level atomic), post-release buffer_inv dropped
# speedup vs baseline: 1.0089x; 1.0089x over previous
; __device__ __forceinline__ unsigned xb_ld(unsigned* p)              { return __hip_atomic_load(p, __ATOMIC_RELAXED, __HIP_MEMORY_SCOPE_AGENT); }
; __device__ __forceinline__ unsigned xb_add(unsigned* p, unsigned v) { return __hip_atomic_fetch_add(p, v, __ATOMIC_RELAXED, __HIP_MEMORY_SCOPE_AGENT); }
; #define XB_SPIN(cond, bar) do { unsigned _sp = 0; while (cond) { __builtin_amdgcn_s_sleep(1); \
;     if ((++_sp & 255u) == 0u) { if (xb_ld(&(bar)[XB_TMO])) break; if (_sp > XB_SPIN_CAP) { atomicAdd(&(bar)[XB_TMO], 1u); break; } } } } while (0)
; __device__ __forceinline__ void xcd_barrier(const XcdBarrier& b) {
;     ...
;         const unsigned old = xb_add(&bar[XB_XSUB(b.x)], 1u);
;         const unsigned gen = old / nloc;
;         if (old + 1u == (gen + 1u) * nloc) {
;             __builtin_amdgcn_fence(__ATOMIC_RELEASE, "agent");
;             asm volatile("s_waitcnt vmcnt(0)" ::: "memory");
;             const unsigned og = xb_add(&bar[XB_TOP], 1u);
;             const unsigned tg = og / nx;
;             if (og + 1u == (tg + 1u) * nx) xb_add(&bar[XB_TOPGEN], 1u);
;             else XB_SPIN(xb_ld(&bar[XB_TOPGEN]) == tg, bar);
;             __builtin_amdgcn_fence(__ATOMIC_ACQUIRE, "agent");
;             xb_add(&bar[XB_XGEN(b.x)], 1u);
;             asm volatile("s_waitcnt vmcnt(0)" ::: "memory");
;         } else {
;             XB_SPIN(xb_ld(&bar[XB_XGEN(b.x)]) == gen, bar);
;             __builtin_amdgcn_fence(__ATOMIC_ACQUIRE, "agent");
;             asm volatile("s_waitcnt vmcnt(0)" ::: "memory");
.LBB0_412:
	s_or_b64 exec, exec, s[8:9]
	v_cvt_f32_u32_e32 v7, v5
	s_waitcnt vmcnt(0)
	v_readfirstlane_b32 s6, v6
	v_sub_u32_e32 v6, 0, v5
	v_rcp_iflag_f32_e32 v7, v7
	v_add_u32_e32 v8, s6, v2
	v_mul_f32_e32 v7, 0x4f7ffffe, v7
	v_cvt_u32_f32_e32 v7, v7
	v_mul_lo_u32 v2, v6, v7
	v_mul_hi_u32 v2, v7, v2
	v_add_u32_e32 v2, v7, v2
	v_mul_hi_u32 v2, v8, v2
	v_mul_lo_u32 v6, v2, v5
	v_sub_u32_e32 v6, v8, v6
	v_add_u32_e32 v7, 1, v2
	v_cmp_ge_u32_e32 vcc, v6, v5
	s_nop 1
	v_cndmask_b32_e32 v2, v2, v7, vcc
	v_sub_u32_e32 v7, v6, v5
	v_cndmask_b32_e32 v6, v6, v7, vcc
	v_add_u32_e32 v7, 1, v2
	v_cmp_ge_u32_e32 vcc, v6, v5
	v_add_u32_e32 v6, 1, v8
	s_nop 0
	v_cndmask_b32_e32 v2, v2, v7, vcc
	v_mul_lo_u32 v7, v5, v2
	v_add_u32_e32 v5, v7, v5
	v_cmp_ne_u32_e32 vcc, v6, v5
	s_and_saveexec_b64 s[6:7], vcc
	s_xor_b64 s[6:7], exec, s[6:7]
	s_cbranch_execz .LBB0_426
	s_add_i32 s30, s40, 0x900
	s_lshl_b64 s[8:9], s[30:31], 2
	s_add_u32 s46, s34, s8
	s_addc_u32 s47, s35, s9
	s_waitcnt lgkmcnt(0)
	buffer_inv sc1
	global_load_dword v4, v3, s[46:47] sc1
	s_waitcnt vmcnt(0)
	v_cmp_eq_u32_e32 vcc, v4, v2
	s_and_saveexec_b64 s[8:9], vcc
	s_cbranch_execz .LBB0_425
	s_add_u32 s14, s4, 0x80200
	s_addc_u32 s15, s5, 0
	s_mov_b32 s30, 1
	s_mov_b64 s[52:53], 0
	s_branch .LBB0_416

; __device__ __forceinline__ unsigned xb_ld(unsigned* p)              { return __hip_atomic_load(p, __ATOMIC_RELAXED, __HIP_MEMORY_SCOPE_AGENT); }
; __device__ __forceinline__ unsigned xb_add(unsigned* p, unsigned v) { return __hip_atomic_fetch_add(p, v, __ATOMIC_RELAXED, __HIP_MEMORY_SCOPE_AGENT); }
; #define XB_SPIN(cond, bar) do { unsigned _sp = 0; while (cond) { __builtin_amdgcn_s_sleep(1); \
;     if ((++_sp & 255u) == 0u) { if (xb_ld(&(bar)[XB_TMO])) break; if (_sp > XB_SPIN_CAP) { atomicAdd(&(bar)[XB_TMO], 1u); break; } } } } while (0)
; __device__ __forceinline__ void xcd_barrier(const XcdBarrier& b) {
;     ...
;         if (old + 1u == (gen + 1u) * nloc) {
;             __builtin_amdgcn_fence(__ATOMIC_RELEASE, "agent");
;             asm volatile("s_waitcnt vmcnt(0)" ::: "memory");
;             const unsigned og = xb_add(&bar[XB_TOP], 1u);
;             const unsigned tg = og / nx;
;             if (og + 1u == (tg + 1u) * nx) xb_add(&bar[XB_TOPGEN], 1u);
;             else XB_SPIN(xb_ld(&bar[XB_TOPGEN]) == tg, bar);
;             __builtin_amdgcn_fence(__ATOMIC_ACQUIRE, "agent");
;             xb_add(&bar[XB_XGEN(b.x)], 1u);
;             asm volatile("s_waitcnt vmcnt(0)" ::: "memory");
;         } else {
;             XB_SPIN(xb_ld(&bar[XB_XGEN(b.x)]) == gen, bar);
;             __builtin_amdgcn_fence(__ATOMIC_ACQUIRE, "agent");
;             asm volatile("s_waitcnt vmcnt(0)" ::: "memory");
.LBB0_425:
	s_or_b64 exec, exec, s[8:9]
	s_waitcnt vmcnt(0)
	s_waitcnt vmcnt(0)
.LBB0_426:
	s_andn2_saveexec_b64 s[6:7], s[6:7]
	s_cbranch_execz .LBB0_446
	s_mov_b64 s[6:7], exec
	buffer_wbl2 sc1
	v_mov_b32_e32 v19, v2
	s_lshl_b32 s100, s40, 2
	s_add_u32 s100, s100, 0x82400
	s_add_u32 s100, s4, s100
	s_addc_u32 s101, s5, 0
	s_waitcnt lgkmcnt(0)
	s_waitcnt vmcnt(0)
	v_mbcnt_lo_u32_b32 v2, s6, 0
	v_mbcnt_hi_u32_b32 v2, s7, v2
	v_cmp_eq_u32_e32 vcc, 0, v2
	s_and_saveexec_b64 s[8:9], vcc
	s_cbranch_execz .LBB0_429
	s_bcnt1_i32_b64 s6, s[6:7]
	v_mov_b32_e32 v5, s6
	global_atomic_add v5, v197, v5, s[4:5] offset:1024 sc0
	buffer_inv sc1

; __device__ __forceinline__ unsigned xb_add(unsigned* p, unsigned v) { return __hip_atomic_fetch_add(p, v, __ATOMIC_RELAXED, __HIP_MEMORY_SCOPE_AGENT); }
; __device__ __forceinline__ void xcd_barrier(const XcdBarrier& b) {
;     ...
;             __builtin_amdgcn_fence(__ATOMIC_ACQUIRE, "agent");
;             xb_add(&bar[XB_XGEN(b.x)], 1u);
;             asm volatile("s_waitcnt vmcnt(0)" ::: "memory");
.LBB0_443:
	s_or_b64 exec, exec, s[4:5]
	s_mov_b64 s[4:5], exec
	v_mbcnt_lo_u32_b32 v2, s4, 0
	v_mbcnt_hi_u32_b32 v2, s5, v2
	v_cmp_eq_u32_e32 vcc, 0, v2
	s_waitcnt vmcnt(0)
	s_and_saveexec_b64 s[6:7], vcc
	s_cbranch_execz .LBB0_445
	s_add_i32 s30, s40, 0x900
	s_lshl_b64 s[8:9], s[30:31], 2
	s_add_u32 s8, s34, s8
	s_addc_u32 s9, s35, s9
	s_bcnt1_i32_b64 s4, s[4:5]
	v_mov_b32_e32 v2, s4

; __device__ __forceinline__ unsigned xb_ld(unsigned* p)              { return __hip_atomic_load(p, __ATOMIC_RELAXED, __HIP_MEMORY_SCOPE_AGENT); }
; __device__ __forceinline__ unsigned xb_add(unsigned* p, unsigned v) { return __hip_atomic_fetch_add(p, v, __ATOMIC_RELAXED, __HIP_MEMORY_SCOPE_AGENT); }
; #define XB_SPIN(cond, bar) do { unsigned _sp = 0; while (cond) { __builtin_amdgcn_s_sleep(1); \
;     if ((++_sp & 255u) == 0u) { if (xb_ld(&(bar)[XB_TMO])) break; if (_sp > XB_SPIN_CAP) { atomicAdd(&(bar)[XB_TMO], 1u); break; } } } } while (0)
; __device__ __forceinline__ void xcd_barrier(const XcdBarrier& b) {
;     ...
;         const unsigned old = xb_add(&bar[XB_XSUB(b.x)], 1u);
;         const unsigned gen = old / nloc;
;         if (old + 1u == (gen + 1u) * nloc) {
;             __builtin_amdgcn_fence(__ATOMIC_RELEASE, "agent");
;             asm volatile("s_waitcnt vmcnt(0)" ::: "memory");
;             const unsigned og = xb_add(&bar[XB_TOP], 1u);
;             const unsigned tg = og / nx;
;             if (og + 1u == (tg + 1u) * nx) xb_add(&bar[XB_TOPGEN], 1u);
;             else XB_SPIN(xb_ld(&bar[XB_TOPGEN]) == tg, bar);
;             __builtin_amdgcn_fence(__ATOMIC_ACQUIRE, "agent");
;             xb_add(&bar[XB_XGEN(b.x)], 1u);
;             asm volatile("s_waitcnt vmcnt(0)" ::: "memory");
;         } else {
;             XB_SPIN(xb_ld(&bar[XB_XGEN(b.x)]) == gen, bar);
;             __builtin_amdgcn_fence(__ATOMIC_ACQUIRE, "agent");
;             asm volatile("s_waitcnt vmcnt(0)" ::: "memory");
.LBB0_654:
	s_or_b64 exec, exec, s[6:7]
	v_cvt_f32_u32_e32 v7, v5
	s_waitcnt vmcnt(0)
	v_readfirstlane_b32 s4, v6
	v_sub_u32_e32 v6, 0, v5
	v_rcp_iflag_f32_e32 v7, v7
	v_add_u32_e32 v8, s4, v2
	v_mul_f32_e32 v7, 0x4f7ffffe, v7
	v_cvt_u32_f32_e32 v7, v7
	v_mul_lo_u32 v2, v6, v7
	v_mul_hi_u32 v2, v7, v2
	v_add_u32_e32 v2, v7, v2
	v_mul_hi_u32 v2, v8, v2
	v_mul_lo_u32 v6, v2, v5
	v_sub_u32_e32 v6, v8, v6
	v_add_u32_e32 v7, 1, v2
	v_cmp_ge_u32_e32 vcc, v6, v5
	s_nop 1
	v_cndmask_b32_e32 v2, v2, v7, vcc
	v_sub_u32_e32 v7, v6, v5
	v_cndmask_b32_e32 v6, v6, v7, vcc
	v_add_u32_e32 v7, 1, v2
	v_cmp_ge_u32_e32 vcc, v6, v5
	v_add_u32_e32 v6, 1, v8
	s_nop 0
	v_cndmask_b32_e32 v2, v2, v7, vcc
	v_mul_lo_u32 v7, v5, v2
	v_add_u32_e32 v5, v7, v5
	v_cmp_ne_u32_e32 vcc, v6, v5
	s_and_saveexec_b64 s[4:5], vcc
	s_xor_b64 s[4:5], exec, s[4:5]
	s_cbranch_execz .LBB0_668
	s_add_i32 s30, s40, 0x900
	s_lshl_b64 s[6:7], s[30:31], 2
	s_add_u32 s14, s34, s6
	s_addc_u32 s15, s35, s7
	s_waitcnt lgkmcnt(0)
	buffer_inv sc1
	global_load_dword v4, v3, s[14:15] sc1
	s_waitcnt vmcnt(0)
	v_cmp_eq_u32_e32 vcc, v4, v2
	s_and_saveexec_b64 s[6:7], vcc
	s_cbranch_execz .LBB0_667
	s_add_u32 s8, s2, 0x80200
	s_addc_u32 s9, s3, 0
	s_mov_b32 s30, 1
	s_mov_b64 s[46:47], 0
	s_branch .LBB0_658

; __device__ __forceinline__ unsigned xb_ld(unsigned* p)              { return __hip_atomic_load(p, __ATOMIC_RELAXED, __HIP_MEMORY_SCOPE_AGENT); }
; __device__ __forceinline__ unsigned xb_add(unsigned* p, unsigned v) { return __hip_atomic_fetch_add(p, v, __ATOMIC_RELAXED, __HIP_MEMORY_SCOPE_AGENT); }
; #define XB_SPIN(cond, bar) do { unsigned _sp = 0; while (cond) { __builtin_amdgcn_s_sleep(1); \
;     if ((++_sp & 255u) == 0u) { if (xb_ld(&(bar)[XB_TMO])) break; if (_sp > XB_SPIN_CAP) { atomicAdd(&(bar)[XB_TMO], 1u); break; } } } } while (0)
; __device__ __forceinline__ void xcd_barrier(const XcdBarrier& b) {
;     ...
;         if (old + 1u == (gen + 1u) * nloc) {
;             __builtin_amdgcn_fence(__ATOMIC_RELEASE, "agent");
;             asm volatile("s_waitcnt vmcnt(0)" ::: "memory");
;             const unsigned og = xb_add(&bar[XB_TOP], 1u);
;             const unsigned tg = og / nx;
;             if (og + 1u == (tg + 1u) * nx) xb_add(&bar[XB_TOPGEN], 1u);
;             else XB_SPIN(xb_ld(&bar[XB_TOPGEN]) == tg, bar);
;             __builtin_amdgcn_fence(__ATOMIC_ACQUIRE, "agent");
;             xb_add(&bar[XB_XGEN(b.x)], 1u);
;             asm volatile("s_waitcnt vmcnt(0)" ::: "memory");
;         } else {
;             XB_SPIN(xb_ld(&bar[XB_XGEN(b.x)]) == gen, bar);
;             __builtin_amdgcn_fence(__ATOMIC_ACQUIRE, "agent");
;             asm volatile("s_waitcnt vmcnt(0)" ::: "memory");
.LBB0_667:
	s_or_b64 exec, exec, s[6:7]
	s_waitcnt vmcnt(0)
	s_waitcnt vmcnt(0)
.LBB0_668:
	s_andn2_saveexec_b64 s[4:5], s[4:5]
	s_cbranch_execz .LBB0_688
	s_mov_b64 s[4:5], exec
	buffer_wbl2 sc1
	v_mov_b32_e32 v19, v2
	s_lshl_b32 s100, s40, 2
	s_add_u32 s100, s100, 0x82400
	s_add_u32 s100, s2, s100
	s_addc_u32 s101, s3, 0
	s_waitcnt lgkmcnt(0)
	s_waitcnt vmcnt(0)
	v_mbcnt_lo_u32_b32 v2, s4, 0
	v_mbcnt_hi_u32_b32 v2, s5, v2
	v_cmp_eq_u32_e32 vcc, 0, v2
	s_and_saveexec_b64 s[6:7], vcc
	s_cbranch_execz .LBB0_671
	s_bcnt1_i32_b64 s4, s[4:5]
	v_mov_b32_e32 v5, s4
	global_atomic_add v5, v197, v5, s[2:3] offset:1024 sc0
	buffer_inv sc1

; __device__ __forceinline__ unsigned xb_add(unsigned* p, unsigned v) { return __hip_atomic_fetch_add(p, v, __ATOMIC_RELAXED, __HIP_MEMORY_SCOPE_AGENT); }
; __device__ __forceinline__ void xcd_barrier(const XcdBarrier& b) {
;     ...
;             __builtin_amdgcn_fence(__ATOMIC_ACQUIRE, "agent");
;             xb_add(&bar[XB_XGEN(b.x)], 1u);
;             asm volatile("s_waitcnt vmcnt(0)" ::: "memory");
.LBB0_685:
	s_or_b64 exec, exec, s[2:3]
	s_mov_b64 s[2:3], exec
	v_mbcnt_lo_u32_b32 v2, s2, 0
	v_mbcnt_hi_u32_b32 v2, s3, v2
	v_cmp_eq_u32_e32 vcc, 0, v2
	s_waitcnt vmcnt(0)
	s_and_saveexec_b64 s[4:5], vcc
	s_cbranch_execz .LBB0_687
	s_add_i32 s30, s40, 0x900
	s_lshl_b64 s[6:7], s[30:31], 2
	s_add_u32 s6, s34, s6
	s_addc_u32 s7, s35, s7
	s_bcnt1_i32_b64 s2, s[2:3]
	v_mov_b32_e32 v2, s2

; __device__ __forceinline__ unsigned xb_ld(unsigned* p)              { return __hip_atomic_load(p, __ATOMIC_RELAXED, __HIP_MEMORY_SCOPE_AGENT); }
; __device__ __forceinline__ unsigned xb_add(unsigned* p, unsigned v) { return __hip_atomic_fetch_add(p, v, __ATOMIC_RELAXED, __HIP_MEMORY_SCOPE_AGENT); }
; #define XB_SPIN(cond, bar) do { unsigned _sp = 0; while (cond) { __builtin_amdgcn_s_sleep(1); \
;     if ((++_sp & 255u) == 0u) { if (xb_ld(&(bar)[XB_TMO])) break; if (_sp > XB_SPIN_CAP) { atomicAdd(&(bar)[XB_TMO], 1u); break; } } } } while (0)
; __device__ __forceinline__ void xcd_barrier(const XcdBarrier& b) {
;     ...
;         const unsigned old = xb_add(&bar[XB_XSUB(b.x)], 1u);
;         const unsigned gen = old / nloc;
;         if (old + 1u == (gen + 1u) * nloc) {
;             __builtin_amdgcn_fence(__ATOMIC_RELEASE, "agent");
;             asm volatile("s_waitcnt vmcnt(0)" ::: "memory");
;             const unsigned og = xb_add(&bar[XB_TOP], 1u);
;             const unsigned tg = og / nx;
;             if (og + 1u == (tg + 1u) * nx) xb_add(&bar[XB_TOPGEN], 1u);
;             else XB_SPIN(xb_ld(&bar[XB_TOPGEN]) == tg, bar);
;             __builtin_amdgcn_fence(__ATOMIC_ACQUIRE, "agent");
;             xb_add(&bar[XB_XGEN(b.x)], 1u);
;             asm volatile("s_waitcnt vmcnt(0)" ::: "memory");
;         } else {
;             XB_SPIN(xb_ld(&bar[XB_XGEN(b.x)]) == gen, bar);
;             __builtin_amdgcn_fence(__ATOMIC_ACQUIRE, "agent");
;             asm volatile("s_waitcnt vmcnt(0)" ::: "memory");
.LBB0_906:
	s_or_b64 exec, exec, s[6:7]
	v_cvt_f32_u32_e32 v7, v5
	s_waitcnt vmcnt(0)
	v_readfirstlane_b32 s4, v6
	v_sub_u32_e32 v6, 0, v5
	v_rcp_iflag_f32_e32 v7, v7
	v_add_u32_e32 v8, s4, v2
	v_mul_f32_e32 v7, 0x4f7ffffe, v7
	v_cvt_u32_f32_e32 v7, v7
	v_mul_lo_u32 v2, v6, v7
	v_mul_hi_u32 v2, v7, v2
	v_add_u32_e32 v2, v7, v2
	v_mul_hi_u32 v2, v8, v2
	v_mul_lo_u32 v6, v2, v5
	v_sub_u32_e32 v6, v8, v6
	v_add_u32_e32 v7, 1, v2
	v_cmp_ge_u32_e32 vcc, v6, v5
	s_nop 1
	v_cndmask_b32_e32 v2, v2, v7, vcc
	v_sub_u32_e32 v7, v6, v5
	v_cndmask_b32_e32 v6, v6, v7, vcc
	v_add_u32_e32 v7, 1, v2
	v_cmp_ge_u32_e32 vcc, v6, v5
	v_add_u32_e32 v6, 1, v8
	s_nop 0
	v_cndmask_b32_e32 v2, v2, v7, vcc
	v_mul_lo_u32 v7, v5, v2
	v_add_u32_e32 v5, v7, v5
	v_cmp_ne_u32_e32 vcc, v6, v5
	s_and_saveexec_b64 s[4:5], vcc
	s_xor_b64 s[4:5], exec, s[4:5]
	s_cbranch_execz .LBB0_920
	s_add_i32 s6, s40, 0x900
	s_mov_b32 s7, s31
	s_lshl_b64 s[6:7], s[6:7], 2
	s_add_u32 s14, s34, s6
	s_addc_u32 s15, s35, s7
	s_waitcnt lgkmcnt(0)
	buffer_inv sc1
	global_load_dword v4, v3, s[14:15] sc1
	s_waitcnt vmcnt(0)
	v_cmp_eq_u32_e32 vcc, v4, v2
	s_and_saveexec_b64 s[6:7], vcc
	s_cbranch_execz .LBB0_919
	s_add_u32 s8, s2, 0x80200
	s_addc_u32 s9, s3, 0
	s_mov_b32 s41, 1
	s_mov_b64 s[46:47], 0
	s_branch .LBB0_910

; __device__ __forceinline__ unsigned xb_add(unsigned* p, unsigned v) { return __hip_atomic_fetch_add(p, v, __ATOMIC_RELAXED, __HIP_MEMORY_SCOPE_AGENT); }
; __device__ __forceinline__ void xcd_barrier(const XcdBarrier& b) {
;     ...
;             __builtin_amdgcn_fence(__ATOMIC_ACQUIRE, "agent");
;             xb_add(&bar[XB_XGEN(b.x)], 1u);
;             asm volatile("s_waitcnt vmcnt(0)" ::: "memory");
.LBB0_937:
	s_or_b64 exec, exec, s[2:3]
	s_mov_b64 s[2:3], exec
	v_mbcnt_lo_u32_b32 v2, s2, 0
	v_mbcnt_hi_u32_b32 v2, s3, v2
	v_cmp_eq_u32_e32 vcc, 0, v2
	s_waitcnt vmcnt(0)
	s_and_saveexec_b64 s[4:5], vcc
	s_cbranch_execz .LBB0_939
	s_add_i32 s6, s40, 0x900
	s_mov_b32 s7, s31
	s_lshl_b64 s[6:7], s[6:7], 2
	s_add_u32 s6, s34, s6
	s_addc_u32 s7, s35, s7
	s_bcnt1_i32_b64 s2, s[2:3]
	v_mov_b32_e32 v2, s2

; __device__ __forceinline__ unsigned xb_ld(unsigned* p)              { return __hip_atomic_load(p, __ATOMIC_RELAXED, __HIP_MEMORY_SCOPE_AGENT); }
; __device__ __forceinline__ unsigned xb_add(unsigned* p, unsigned v) { return __hip_atomic_fetch_add(p, v, __ATOMIC_RELAXED, __HIP_MEMORY_SCOPE_AGENT); }
; #define XB_SPIN(cond, bar) do { unsigned _sp = 0; while (cond) { __builtin_amdgcn_s_sleep(1); \
;     if ((++_sp & 255u) == 0u) { if (xb_ld(&(bar)[XB_TMO])) break; if (_sp > XB_SPIN_CAP) { atomicAdd(&(bar)[XB_TMO], 1u); break; } } } } while (0)
; __device__ __forceinline__ void xcd_barrier(const XcdBarrier& b) {
;     ...
;         const unsigned old = xb_add(&bar[XB_XSUB(b.x)], 1u);
;         const unsigned gen = old / nloc;
;         if (old + 1u == (gen + 1u) * nloc) {
;             __builtin_amdgcn_fence(__ATOMIC_RELEASE, "agent");
;             asm volatile("s_waitcnt vmcnt(0)" ::: "memory");
;             const unsigned og = xb_add(&bar[XB_TOP], 1u);
;             const unsigned tg = og / nx;
;             if (og + 1u == (tg + 1u) * nx) xb_add(&bar[XB_TOPGEN], 1u);
;             else XB_SPIN(xb_ld(&bar[XB_TOPGEN]) == tg, bar);
;             __builtin_amdgcn_fence(__ATOMIC_ACQUIRE, "agent");
;             xb_add(&bar[XB_XGEN(b.x)], 1u);
;             asm volatile("s_waitcnt vmcnt(0)" ::: "memory");
;         } else {
;             XB_SPIN(xb_ld(&bar[XB_XGEN(b.x)]) == gen, bar);
;             __builtin_amdgcn_fence(__ATOMIC_ACQUIRE, "agent");
;             asm volatile("s_waitcnt vmcnt(0)" ::: "memory");
.LBB0_1099:
	s_or_b64 exec, exec, s[6:7]
	v_cvt_f32_u32_e32 v7, v5
	s_waitcnt vmcnt(0)
	v_readfirstlane_b32 s4, v6
	v_sub_u32_e32 v6, 0, v5
	v_rcp_iflag_f32_e32 v7, v7
	v_add_u32_e32 v8, s4, v2
	v_mul_f32_e32 v7, 0x4f7ffffe, v7
	v_cvt_u32_f32_e32 v7, v7
	v_mul_lo_u32 v2, v6, v7
	v_mul_hi_u32 v2, v7, v2
	v_add_u32_e32 v2, v7, v2
	v_mul_hi_u32 v2, v8, v2
	v_mul_lo_u32 v6, v2, v5
	v_sub_u32_e32 v6, v8, v6
	v_add_u32_e32 v7, 1, v2
	v_cmp_ge_u32_e32 vcc, v6, v5
	s_nop 1
	v_cndmask_b32_e32 v2, v2, v7, vcc
	v_sub_u32_e32 v7, v6, v5
	v_cndmask_b32_e32 v6, v6, v7, vcc
	v_add_u32_e32 v7, 1, v2
	v_cmp_ge_u32_e32 vcc, v6, v5
	v_add_u32_e32 v6, 1, v8
	s_nop 0
	v_cndmask_b32_e32 v2, v2, v7, vcc
	v_mul_lo_u32 v7, v5, v2
	v_add_u32_e32 v5, v7, v5
	v_cmp_ne_u32_e32 vcc, v6, v5
	s_and_saveexec_b64 s[4:5], vcc
	s_xor_b64 s[4:5], exec, s[4:5]
	s_cbranch_execz .LBB0_1113
	s_add_i32 s6, s40, 0x900
	s_mov_b32 s7, s31
	s_lshl_b64 s[6:7], s[6:7], 2
	s_add_u32 s46, s34, s6
	s_addc_u32 s47, s35, s7
	s_waitcnt lgkmcnt(0)
	buffer_inv sc1
	global_load_dword v4, v3, s[46:47] sc1
	s_waitcnt vmcnt(0)
	v_cmp_eq_u32_e32 vcc, v4, v2
	s_and_saveexec_b64 s[6:7], vcc
	s_cbranch_execz .LBB0_1112
	s_add_u32 s14, s2, 0x80200
	s_addc_u32 s15, s3, 0
	s_mov_b32 s41, 1
	s_mov_b64 s[52:53], 0
	s_branch .LBB0_1103

; __device__ __forceinline__ unsigned xb_ld(unsigned* p)              { return __hip_atomic_load(p, __ATOMIC_RELAXED, __HIP_MEMORY_SCOPE_AGENT); }
; __device__ __forceinline__ unsigned xb_add(unsigned* p, unsigned v) { return __hip_atomic_fetch_add(p, v, __ATOMIC_RELAXED, __HIP_MEMORY_SCOPE_AGENT); }
; #define XB_SPIN(cond, bar) do { unsigned _sp = 0; while (cond) { __builtin_amdgcn_s_sleep(1); \
;     if ((++_sp & 255u) == 0u) { if (xb_ld(&(bar)[XB_TMO])) break; if (_sp > XB_SPIN_CAP) { atomicAdd(&(bar)[XB_TMO], 1u); break; } } } } while (0)
; __device__ __forceinline__ void xcd_barrier(const XcdBarrier& b) {
;     ...
;         const unsigned old = xb_add(&bar[XB_XSUB(b.x)], 1u);
;         const unsigned gen = old / nloc;
;         if (old + 1u == (gen + 1u) * nloc) {
;             __builtin_amdgcn_fence(__ATOMIC_RELEASE, "agent");
;             asm volatile("s_waitcnt vmcnt(0)" ::: "memory");
;             const unsigned og = xb_add(&bar[XB_TOP], 1u);
;             const unsigned tg = og / nx;
;             if (og + 1u == (tg + 1u) * nx) xb_add(&bar[XB_TOPGEN], 1u);
;             else XB_SPIN(xb_ld(&bar[XB_TOPGEN]) == tg, bar);
;             __builtin_amdgcn_fence(__ATOMIC_ACQUIRE, "agent");
;             xb_add(&bar[XB_XGEN(b.x)], 1u);
;             asm volatile("s_waitcnt vmcnt(0)" ::: "memory");
;         } else {
;             XB_SPIN(xb_ld(&bar[XB_XGEN(b.x)]) == gen, bar);
;             __builtin_amdgcn_fence(__ATOMIC_ACQUIRE, "agent");
;             asm volatile("s_waitcnt vmcnt(0)" ::: "memory");
.LBB0_1167:
	s_or_b64 exec, exec, s[14:15]
	v_cvt_f32_u32_e32 v7, v5
	s_waitcnt vmcnt(0)
	v_readfirstlane_b32 s6, v6
	v_sub_u32_e32 v6, 0, v5
	v_rcp_iflag_f32_e32 v7, v7
	v_add_u32_e32 v8, s6, v2
	v_mul_f32_e32 v7, 0x4f7ffffe, v7
	v_cvt_u32_f32_e32 v7, v7
	v_mul_lo_u32 v2, v6, v7
	v_mul_hi_u32 v2, v7, v2
	v_add_u32_e32 v2, v7, v2
	v_mul_hi_u32 v2, v8, v2
	v_mul_lo_u32 v6, v2, v5
	v_sub_u32_e32 v6, v8, v6
	v_add_u32_e32 v7, 1, v2
	v_cmp_ge_u32_e32 vcc, v6, v5
	s_nop 1
	v_cndmask_b32_e32 v2, v2, v7, vcc
	v_sub_u32_e32 v7, v6, v5
	v_cndmask_b32_e32 v6, v6, v7, vcc
	v_add_u32_e32 v7, 1, v2
	v_cmp_ge_u32_e32 vcc, v6, v5
	v_add_u32_e32 v6, 1, v8
	s_nop 0
	v_cndmask_b32_e32 v2, v2, v7, vcc
	v_mul_lo_u32 v7, v5, v2
	v_add_u32_e32 v5, v7, v5
	v_cmp_ne_u32_e32 vcc, v6, v5
	s_and_saveexec_b64 s[6:7], vcc
	s_xor_b64 s[6:7], exec, s[6:7]
	s_cbranch_execz .LBB0_1181
	s_add_i32 s10, s40, 0x900
	s_mov_b32 s11, s31
	s_lshl_b64 s[10:11], s[10:11], 2
	s_add_u32 s52, s34, s10
	s_addc_u32 s53, s35, s11
	s_waitcnt lgkmcnt(0)
	buffer_inv sc1
	global_load_dword v4, v3, s[52:53] sc1
	s_waitcnt vmcnt(0)
	v_cmp_eq_u32_e32 vcc, v4, v2
	s_and_saveexec_b64 s[14:15], vcc
	s_cbranch_execz .LBB0_1180
	s_add_u32 s46, s4, 0x80200
	s_addc_u32 s47, s5, 0
	s_mov_b32 s41, 1
	s_mov_b64 s[58:59], 0
	s_branch .LBB0_1171

; __device__ __forceinline__ unsigned xb_ld(unsigned* p)              { return __hip_atomic_load(p, __ATOMIC_RELAXED, __HIP_MEMORY_SCOPE_AGENT); }
; __device__ __forceinline__ unsigned xb_add(unsigned* p, unsigned v) { return __hip_atomic_fetch_add(p, v, __ATOMIC_RELAXED, __HIP_MEMORY_SCOPE_AGENT); }
; #define XB_SPIN(cond, bar) do { unsigned _sp = 0; while (cond) { __builtin_amdgcn_s_sleep(1); \
;     if ((++_sp & 255u) == 0u) { if (xb_ld(&(bar)[XB_TMO])) break; if (_sp > XB_SPIN_CAP) { atomicAdd(&(bar)[XB_TMO], 1u); break; } } } } while (0)
; __device__ __forceinline__ void xcd_barrier(const XcdBarrier& b) {
;     ...
;         if (old + 1u == (gen + 1u) * nloc) {
;             __builtin_amdgcn_fence(__ATOMIC_RELEASE, "agent");
;             asm volatile("s_waitcnt vmcnt(0)" ::: "memory");
;             const unsigned og = xb_add(&bar[XB_TOP], 1u);
;             const unsigned tg = og / nx;
;             if (og + 1u == (tg + 1u) * nx) xb_add(&bar[XB_TOPGEN], 1u);
;             else XB_SPIN(xb_ld(&bar[XB_TOPGEN]) == tg, bar);
;             __builtin_amdgcn_fence(__ATOMIC_ACQUIRE, "agent");
;             xb_add(&bar[XB_XGEN(b.x)], 1u);
;             asm volatile("s_waitcnt vmcnt(0)" ::: "memory");
;         } else {
;             XB_SPIN(xb_ld(&bar[XB_XGEN(b.x)]) == gen, bar);
;             __builtin_amdgcn_fence(__ATOMIC_ACQUIRE, "agent");
;             asm volatile("s_waitcnt vmcnt(0)" ::: "memory");
.LBB0_1180:
	s_or_b64 exec, exec, s[14:15]
	s_waitcnt vmcnt(0)
	s_waitcnt vmcnt(0)
.LBB0_1181:
	s_andn2_saveexec_b64 s[6:7], s[6:7]
	s_cbranch_execz .LBB0_1201
	s_mov_b64 s[6:7], exec
	buffer_wbl2 sc1
	v_mov_b32_e32 v19, v2
	s_lshl_b32 s100, s40, 2
	s_add_u32 s100, s100, 0x82400
	s_add_u32 s100, s4, s100
	s_addc_u32 s101, s5, 0
	s_waitcnt lgkmcnt(0)
	s_waitcnt vmcnt(0)
	v_mbcnt_lo_u32_b32 v2, s6, 0
	v_mbcnt_hi_u32_b32 v2, s7, v2
	v_cmp_eq_u32_e32 vcc, 0, v2
	s_and_saveexec_b64 s[14:15], vcc
	s_cbranch_execz .LBB0_1184
	s_bcnt1_i32_b64 s6, s[6:7]
	v_mov_b32_e32 v5, s6
	global_atomic_add v5, v197, v5, s[4:5] offset:1024 sc0
	buffer_inv sc1

; __device__ __forceinline__ unsigned xb_add(unsigned* p, unsigned v) { return __hip_atomic_fetch_add(p, v, __ATOMIC_RELAXED, __HIP_MEMORY_SCOPE_AGENT); }
; __device__ __forceinline__ void xcd_barrier(const XcdBarrier& b) {
;     ...
;             __builtin_amdgcn_fence(__ATOMIC_ACQUIRE, "agent");
;             xb_add(&bar[XB_XGEN(b.x)], 1u);
;             asm volatile("s_waitcnt vmcnt(0)" ::: "memory");
.LBB0_1198:
	s_or_b64 exec, exec, s[4:5]
	s_mov_b64 s[4:5], exec
	v_mbcnt_lo_u32_b32 v2, s4, 0
	v_mbcnt_hi_u32_b32 v2, s5, v2
	v_cmp_eq_u32_e32 vcc, 0, v2
	s_waitcnt vmcnt(0)
	s_and_saveexec_b64 s[6:7], vcc
	s_cbranch_execz .LBB0_1200
	s_add_i32 s10, s40, 0x900
	s_mov_b32 s11, s31
	s_lshl_b64 s[10:11], s[10:11], 2
	s_add_u32 s10, s34, s10
	s_addc_u32 s11, s35, s11
	s_bcnt1_i32_b64 s4, s[4:5]
	v_mov_b32_e32 v2, s4

; __device__ __forceinline__ unsigned xb_ld(unsigned* p)              { return __hip_atomic_load(p, __ATOMIC_RELAXED, __HIP_MEMORY_SCOPE_AGENT); }
; __device__ __forceinline__ unsigned xb_add(unsigned* p, unsigned v) { return __hip_atomic_fetch_add(p, v, __ATOMIC_RELAXED, __HIP_MEMORY_SCOPE_AGENT); }
; #define XB_SPIN(cond, bar) do { unsigned _sp = 0; while (cond) { __builtin_amdgcn_s_sleep(1); \
;     if ((++_sp & 255u) == 0u) { if (xb_ld(&(bar)[XB_TMO])) break; if (_sp > XB_SPIN_CAP) { atomicAdd(&(bar)[XB_TMO], 1u); break; } } } } while (0)
; __device__ __forceinline__ void xcd_barrier(const XcdBarrier& b) {
;     ...
;         const unsigned old = xb_add(&bar[XB_XSUB(b.x)], 1u);
;         const unsigned gen = old / nloc;
;         if (old + 1u == (gen + 1u) * nloc) {
;             __builtin_amdgcn_fence(__ATOMIC_RELEASE, "agent");
;             asm volatile("s_waitcnt vmcnt(0)" ::: "memory");
;             const unsigned og = xb_add(&bar[XB_TOP], 1u);
;             const unsigned tg = og / nx;
;             if (og + 1u == (tg + 1u) * nx) xb_add(&bar[XB_TOPGEN], 1u);
;             else XB_SPIN(xb_ld(&bar[XB_TOPGEN]) == tg, bar);
;             __builtin_amdgcn_fence(__ATOMIC_ACQUIRE, "agent");
;             xb_add(&bar[XB_XGEN(b.x)], 1u);
;             asm volatile("s_waitcnt vmcnt(0)" ::: "memory");
;         } else {
;             XB_SPIN(xb_ld(&bar[XB_XGEN(b.x)]) == gen, bar);
;             __builtin_amdgcn_fence(__ATOMIC_ACQUIRE, "agent");
;             asm volatile("s_waitcnt vmcnt(0)" ::: "memory");
.LBB0_1261:
	s_or_b64 exec, exec, s[6:7]
	v_cvt_f32_u32_e32 v7, v5
	s_waitcnt vmcnt(0)
	v_readfirstlane_b32 s4, v6
	v_sub_u32_e32 v6, 0, v5
	v_rcp_iflag_f32_e32 v7, v7
	v_add_u32_e32 v8, s4, v2
	v_mul_f32_e32 v7, 0x4f7ffffe, v7
	v_cvt_u32_f32_e32 v7, v7
	v_mul_lo_u32 v2, v6, v7
	v_mul_hi_u32 v2, v7, v2
	v_add_u32_e32 v2, v7, v2
	v_mul_hi_u32 v2, v8, v2
	v_mul_lo_u32 v6, v2, v5
	v_sub_u32_e32 v6, v8, v6
	v_add_u32_e32 v7, 1, v2
	v_cmp_ge_u32_e32 vcc, v6, v5
	s_nop 1
	v_cndmask_b32_e32 v2, v2, v7, vcc
	v_sub_u32_e32 v7, v6, v5
	v_cndmask_b32_e32 v6, v6, v7, vcc
	v_add_u32_e32 v7, 1, v2
	v_cmp_ge_u32_e32 vcc, v6, v5
	v_add_u32_e32 v6, 1, v8
	s_nop 0
	v_cndmask_b32_e32 v2, v2, v7, vcc
	v_mul_lo_u32 v7, v5, v2
	v_add_u32_e32 v5, v7, v5
	v_cmp_ne_u32_e32 vcc, v6, v5
	s_and_saveexec_b64 s[4:5], vcc
	s_xor_b64 s[4:5], exec, s[4:5]
	s_cbranch_execz .LBB0_1275
	s_add_i32 s30, s40, 0x900
	s_lshl_b64 s[6:7], s[30:31], 2
	s_add_u32 s46, s34, s6
	s_addc_u32 s47, s35, s7
	s_waitcnt lgkmcnt(0)
	buffer_inv sc1
	global_load_dword v4, v3, s[46:47] sc1
	s_waitcnt vmcnt(0)
	v_cmp_eq_u32_e32 vcc, v4, v2
	s_and_saveexec_b64 s[6:7], vcc
	s_cbranch_execz .LBB0_1274
	s_add_u32 s14, s2, 0x80200
	s_addc_u32 s15, s3, 0
	s_mov_b32 s30, 1
	s_mov_b64 s[52:53], 0
	s_branch .LBB0_1265
